# build_tab (thread 0, three phases per layer): both batches of expert-count loads issued together
# baseline (speedup 1.0000x reference)
; #define LAS __attribute__((address_space(3)))
; __device__ __forceinline__ void build_tab(const int* cnt, LAS int* TAB, const int tid) {
;     if (tid == 0) { int s = 0; for (int e = 0; e < NEXP; ++e) { TAB[e] = s; s += (cnt[e] + 255) >> 8; } TAB[NEXP] = s; }
;     __syncthreads();
; }
; __device__ __forceinline__ void run_phase(const Args& a, const int ph, LAS unsigned char* lds, const int tid, const int rpt) {
;     ...
;             } else if (sp == 8) {
;                 build_tab(cnt, TAB, tid);
.LBB0_18:
	s_mov_b32 s0, s13
	v_readlane_b32 s16, v254, 46
	v_mbcnt_lo_u32_b32 v0, -1, s0
	v_mbcnt_hi_u32_b32 v0, -1, v0
	v_readlane_b32 s0, v251, 13
	v_readlane_b32 s17, v254, 47
	s_and_b64 vcc, exec, s[16:17]
	v_add_u32_e32 v168, s0, v0
	v_readlane_b32 s0, v251, 14
	v_readlane_b32 s1, v251, 15
	s_load_dword s12, s[0:1], 0x0
	s_mov_b64 s[0:1], -1
	v_and_b32_e32 v248, 63, v168
	v_readfirstlane_b32 s71, v168
	s_waitcnt lgkmcnt(0)
	s_lshl_b32 s14, s12, 3
	v_writelane_b32 v249, s12, 49
	s_cbranch_vccz .LBB0_391
	v_readlane_b32 s12, v254, 48
	s_mov_b64 s[16:17], 0
	s_mov_b64 s[48:49], 0
	s_cmp_lt_i32 s12, 4
	v_writelane_b32 v249, s16, 50
	s_nop 1
	v_writelane_b32 v249, s17, 51
	s_cbranch_scc1 .LBB0_170
	v_readlane_b32 s0, v254, 48
	s_cmp_gt_i32 s0, 5
	s_cbranch_scc0 .LBB0_32
	s_cmp_gt_i32 s0, 6
	s_cbranch_scc0 .LBB0_64
	s_cmp_gt_i32 s0, 7
	s_cbranch_scc0 .LBB0_66
	s_cmp_eq_u32 s0, 8
	s_mov_b64 s[0:1], -1
	s_cbranch_scc0 .LBB0_69
	v_cmp_eq_u32_e32 vcc, 0, v168
	s_and_saveexec_b64 s[0:1], vcc
	s_cbranch_execz .LBB0_26
	v_readlane_b32 s16, v254, 49
	v_readlane_b32 s17, v254, 50
	s_nop 4
	global_load_dwordx4 v[0:3], v33, s[16:17] offset:48
	global_load_dwordx4 v[4:7], v33, s[16:17] offset:32
	global_load_dwordx4 v[8:11], v33, s[16:17] offset:16
	global_load_dwordx4 v[12:15], v33, s[16:17]
	global_load_dwordx4 v[192:195], v33, s[16:17] offset:112
	global_load_dwordx4 v[196:199], v33, s[16:17] offset:96
	global_load_dwordx4 v[200:203], v33, s[16:17] offset:80
	global_load_dwordx4 v[212:215], v33, s[16:17] offset:64
	v_readlane_b32 s12, v253, 55
	s_waitcnt vmcnt(0)
	v_mov_b32_e32 v16, v33
	s_waitcnt vmcnt(3)
	v_add_u32_e32 v0, 0xff, v0
	s_waitcnt vmcnt(2)
	v_add_u32_e32 v4, 0xff, v4
	s_waitcnt vmcnt(1)
	v_add_u32_e32 v8, 0xff, v8
	s_waitcnt vmcnt(0)
	v_add_u32_e32 v12, 0xff, v12
	v_ashrrev_i32_e32 v17, 8, v12
	v_add_u32_e32 v12, 0xff, v13
	v_ashrrev_i32_e32 v12, 8, v12
	v_add_u32_e32 v18, v12, v17
	v_add_u32_e32 v12, 0xff, v14
	v_ashrrev_i32_e32 v12, 8, v12
	v_add_u32_e32 v19, v12, v18
	v_mov_b32_e32 v12, s12
	ds_write_b128 v12, v[16:19]
	v_add_u32_e32 v12, 0xff, v15
	v_ashrrev_i32_e32 v12, 8, v12
	v_add_u32_e32 v12, v12, v19
	v_ashrrev_i32_e32 v8, 8, v8
	v_add_u32_e32 v13, v8, v12
	v_add_u32_e32 v8, 0xff, v9
	v_ashrrev_i32_e32 v8, 8, v8
	v_add_u32_e32 v14, v8, v13
	v_add_u32_e32 v8, 0xff, v10
	v_ashrrev_i32_e32 v8, 8, v8
	v_readlane_b32 s12, v253, 56
	v_add_u32_e32 v15, v8, v14
	v_ashrrev_i32_e32 v4, 8, v4
	v_mov_b32_e32 v8, s12
	ds_write_b128 v8, v[12:15]
	v_add_u32_e32 v8, 0xff, v11
	v_ashrrev_i32_e32 v8, 8, v8
	v_add_u32_e32 v8, v8, v15
	v_add_u32_e32 v9, v4, v8
	v_add_u32_e32 v4, 0xff, v5
	v_ashrrev_i32_e32 v4, 8, v4
	v_add_u32_e32 v10, v4, v9
	v_add_u32_e32 v4, 0xff, v6
	v_ashrrev_i32_e32 v4, 8, v4
	v_readlane_b32 s12, v253, 57
	v_add_u32_e32 v11, v4, v10
	v_ashrrev_i32_e32 v0, 8, v0
	v_mov_b32_e32 v4, s12
	ds_write_b128 v4, v[8:11]
	v_add_u32_e32 v4, 0xff, v7
	v_ashrrev_i32_e32 v4, 8, v4
	v_add_u32_e32 v4, v4, v11
	v_add_u32_e32 v5, v0, v4
	v_add_u32_e32 v0, 0xff, v1
	v_ashrrev_i32_e32 v0, 8, v0
	v_add_u32_e32 v6, v0, v5
	v_add_u32_e32 v0, 0xff, v2
	v_ashrrev_i32_e32 v0, 8, v0
	v_readlane_b32 s12, v253, 58
	v_add_u32_e32 v7, v0, v6
	s_nop 0
	v_mov_b32_e32 v0, s12
	ds_write_b128 v0, v[4:7]
	v_add_u32_e32 v0, 0xff, v3
	v_ashrrev_i32_e32 v0, 8, v0
	v_add_u32_e32 v12, v0, v7
	v_mov_b64_e32 v[0:1], v[192:193]
	v_mov_b64_e32 v[2:3], v[194:195]
	v_mov_b64_e32 v[4:5], v[196:197]
	v_mov_b64_e32 v[6:7], v[198:199]
	v_mov_b64_e32 v[8:9], v[200:201]
	v_mov_b64_e32 v[10:11], v[202:203]
	v_mov_b64_e32 v[14:15], v[212:213]
	v_mov_b64_e32 v[16:17], v[214:215]
	v_readlane_b32 s12, v253, 59
	s_waitcnt vmcnt(3)
	v_add_u32_e32 v0, 0xff, v0
	s_waitcnt vmcnt(2)
	v_add_u32_e32 v4, 0xff, v4
	s_waitcnt vmcnt(1)
	v_add_u32_e32 v8, 0xff, v8
	s_waitcnt vmcnt(0)
	v_add_u32_e32 v13, 0xff, v14
	v_ashrrev_i32_e32 v13, 8, v13
	v_add_u32_e32 v14, 0xff, v15
	v_add_u32_e32 v13, v13, v12
	v_ashrrev_i32_e32 v14, 8, v14
	v_add_u32_e32 v15, 0xff, v16
	v_add_u32_e32 v14, v14, v13
	v_ashrrev_i32_e32 v15, 8, v15
	v_add_u32_e32 v15, v15, v14
	v_mov_b32_e32 v16, s12
	ds_write_b128 v16, v[12:15]
	v_add_u32_e32 v12, 0xff, v17
	v_ashrrev_i32_e32 v12, 8, v12
	v_add_u32_e32 v12, v12, v15
	v_ashrrev_i32_e32 v8, 8, v8
	v_add_u32_e32 v13, v8, v12
	v_add_u32_e32 v8, 0xff, v9
	v_ashrrev_i32_e32 v8, 8, v8
	v_add_u32_e32 v14, v8, v13
	v_add_u32_e32 v8, 0xff, v10
	v_ashrrev_i32_e32 v8, 8, v8
	v_readlane_b32 s12, v253, 60
	v_add_u32_e32 v15, v8, v14
	v_ashrrev_i32_e32 v4, 8, v4
	v_mov_b32_e32 v8, s12
	ds_write_b128 v8, v[12:15]
	v_add_u32_e32 v8, 0xff, v11
	v_ashrrev_i32_e32 v8, 8, v8
	v_add_u32_e32 v8, v8, v15
	v_add_u32_e32 v9, v4, v8
	v_add_u32_e32 v4, 0xff, v5
	v_ashrrev_i32_e32 v4, 8, v4
	v_add_u32_e32 v10, v4, v9
	v_add_u32_e32 v4, 0xff, v6
	v_ashrrev_i32_e32 v4, 8, v4
	v_readlane_b32 s12, v253, 61
	v_add_u32_e32 v11, v4, v10
	v_ashrrev_i32_e32 v0, 8, v0
	v_mov_b32_e32 v4, s12
	ds_write_b128 v4, v[8:11]
	v_add_u32_e32 v4, 0xff, v7
	v_ashrrev_i32_e32 v4, 8, v4
	v_add_u32_e32 v4, v4, v11
	v_add_u32_e32 v5, v0, v4
	v_add_u32_e32 v0, 0xff, v1
	v_ashrrev_i32_e32 v0, 8, v0
	v_add_u32_e32 v6, v0, v5
	v_add_u32_e32 v0, 0xff, v2
	v_ashrrev_i32_e32 v0, 8, v0
	v_readlane_b32 s12, v253, 62
	v_add_u32_e32 v7, v0, v6
	s_nop 0
	v_mov_b32_e32 v0, s12
	ds_write_b128 v0, v[4:7]
	v_add_u32_e32 v0, 0xff, v3
	v_ashrrev_i32_e32 v0, 8, v0
	v_readlane_b32 s12, v253, 63
	v_add_u32_e32 v0, v0, v7
	s_nop 0
	v_mov_b32_e32 v1, s12
	ds_write_b32 v1, v0

; #define LAS __attribute__((address_space(3)))
; __device__ __forceinline__ void build_tab(const int* cnt, LAS int* TAB, const int tid) {
;     if (tid == 0) { int s = 0; for (int e = 0; e < NEXP; ++e) { TAB[e] = s; s += (cnt[e] + 255) >> 8; } TAB[NEXP] = s; }
;     __syncthreads();
; }
; __device__ __forceinline__ void run_phase(const Args& a, const int ph, LAS unsigned char* lds, const int tid, const int rpt) {
;     ...
;             } else if (sp == 7) {
;                 build_tab(cnt, TAB, tid);
.LBB0_70:
	v_cmp_eq_u32_e32 vcc, 0, v168
	s_and_saveexec_b64 s[0:1], vcc
	s_cbranch_execz .LBB0_72
	v_readlane_b32 s16, v254, 49
	v_readlane_b32 s17, v254, 50
	s_nop 4
	global_load_dwordx4 v[0:3], v33, s[16:17] offset:48
	global_load_dwordx4 v[4:7], v33, s[16:17] offset:32
	global_load_dwordx4 v[8:11], v33, s[16:17] offset:16
	global_load_dwordx4 v[12:15], v33, s[16:17]
	global_load_dwordx4 v[192:195], v33, s[16:17] offset:112
	global_load_dwordx4 v[196:199], v33, s[16:17] offset:96
	global_load_dwordx4 v[200:203], v33, s[16:17] offset:80
	global_load_dwordx4 v[212:215], v33, s[16:17] offset:64
	v_readlane_b32 s12, v253, 55
	s_waitcnt vmcnt(0)
	v_mov_b32_e32 v16, v33
	s_waitcnt vmcnt(3)
	v_add_u32_e32 v0, 0xff, v0
	s_waitcnt vmcnt(2)
	v_add_u32_e32 v4, 0xff, v4
	s_waitcnt vmcnt(1)
	v_add_u32_e32 v8, 0xff, v8
	s_waitcnt vmcnt(0)
	v_add_u32_e32 v12, 0xff, v12
	v_ashrrev_i32_e32 v17, 8, v12
	v_add_u32_e32 v12, 0xff, v13
	v_ashrrev_i32_e32 v12, 8, v12
	v_add_u32_e32 v18, v12, v17
	v_add_u32_e32 v12, 0xff, v14
	v_ashrrev_i32_e32 v12, 8, v12
	v_add_u32_e32 v19, v12, v18
	v_mov_b32_e32 v12, s12
	ds_write_b128 v12, v[16:19]
	v_add_u32_e32 v12, 0xff, v15
	v_ashrrev_i32_e32 v12, 8, v12
	v_add_u32_e32 v12, v12, v19
	v_ashrrev_i32_e32 v8, 8, v8
	v_add_u32_e32 v13, v8, v12
	v_add_u32_e32 v8, 0xff, v9
	v_ashrrev_i32_e32 v8, 8, v8
	v_add_u32_e32 v14, v8, v13
	v_add_u32_e32 v8, 0xff, v10
	v_ashrrev_i32_e32 v8, 8, v8
	v_readlane_b32 s12, v253, 56
	v_add_u32_e32 v15, v8, v14
	v_ashrrev_i32_e32 v4, 8, v4
	v_mov_b32_e32 v8, s12
	ds_write_b128 v8, v[12:15]
	v_add_u32_e32 v8, 0xff, v11
	v_ashrrev_i32_e32 v8, 8, v8
	v_add_u32_e32 v8, v8, v15
	v_add_u32_e32 v9, v4, v8
	v_add_u32_e32 v4, 0xff, v5
	v_ashrrev_i32_e32 v4, 8, v4
	v_add_u32_e32 v10, v4, v9
	v_add_u32_e32 v4, 0xff, v6
	v_ashrrev_i32_e32 v4, 8, v4
	v_readlane_b32 s12, v253, 57
	v_add_u32_e32 v11, v4, v10
	v_ashrrev_i32_e32 v0, 8, v0
	v_mov_b32_e32 v4, s12
	ds_write_b128 v4, v[8:11]
	v_add_u32_e32 v4, 0xff, v7
	v_ashrrev_i32_e32 v4, 8, v4
	v_add_u32_e32 v4, v4, v11
	v_add_u32_e32 v5, v0, v4
	v_add_u32_e32 v0, 0xff, v1
	v_ashrrev_i32_e32 v0, 8, v0
	v_add_u32_e32 v6, v0, v5
	v_add_u32_e32 v0, 0xff, v2
	v_ashrrev_i32_e32 v0, 8, v0
	v_readlane_b32 s12, v253, 58
	v_add_u32_e32 v7, v0, v6
	s_nop 0
	v_mov_b32_e32 v0, s12
	ds_write_b128 v0, v[4:7]
	v_add_u32_e32 v0, 0xff, v3
	v_ashrrev_i32_e32 v0, 8, v0
	v_add_u32_e32 v12, v0, v7
	v_mov_b64_e32 v[0:1], v[192:193]
	v_mov_b64_e32 v[2:3], v[194:195]
	v_mov_b64_e32 v[4:5], v[196:197]
	v_mov_b64_e32 v[6:7], v[198:199]
	v_mov_b64_e32 v[8:9], v[200:201]
	v_mov_b64_e32 v[10:11], v[202:203]
	v_mov_b64_e32 v[14:15], v[212:213]
	v_mov_b64_e32 v[16:17], v[214:215]
	v_readlane_b32 s12, v253, 59
	s_waitcnt vmcnt(3)
	v_add_u32_e32 v0, 0xff, v0
	s_waitcnt vmcnt(2)
	v_add_u32_e32 v4, 0xff, v4
	s_waitcnt vmcnt(1)
	v_add_u32_e32 v8, 0xff, v8
	s_waitcnt vmcnt(0)
	v_add_u32_e32 v13, 0xff, v14
	v_ashrrev_i32_e32 v13, 8, v13
	v_add_u32_e32 v14, 0xff, v15
	v_add_u32_e32 v13, v13, v12
	v_ashrrev_i32_e32 v14, 8, v14
	v_add_u32_e32 v15, 0xff, v16
	v_add_u32_e32 v14, v14, v13
	v_ashrrev_i32_e32 v15, 8, v15
	v_add_u32_e32 v15, v15, v14
	v_mov_b32_e32 v16, s12
	ds_write_b128 v16, v[12:15]
	v_add_u32_e32 v12, 0xff, v17
	v_ashrrev_i32_e32 v12, 8, v12
	v_add_u32_e32 v12, v12, v15
	v_ashrrev_i32_e32 v8, 8, v8
	v_add_u32_e32 v13, v8, v12
	v_add_u32_e32 v8, 0xff, v9
	v_ashrrev_i32_e32 v8, 8, v8
	v_add_u32_e32 v14, v8, v13
	v_add_u32_e32 v8, 0xff, v10
	v_ashrrev_i32_e32 v8, 8, v8
	v_readlane_b32 s12, v253, 60
	v_add_u32_e32 v15, v8, v14
	v_ashrrev_i32_e32 v4, 8, v4
	v_mov_b32_e32 v8, s12
	ds_write_b128 v8, v[12:15]
	v_add_u32_e32 v8, 0xff, v11
	v_ashrrev_i32_e32 v8, 8, v8
	v_add_u32_e32 v8, v8, v15
	v_add_u32_e32 v9, v4, v8
	v_add_u32_e32 v4, 0xff, v5
	v_ashrrev_i32_e32 v4, 8, v4
	v_add_u32_e32 v10, v4, v9
	v_add_u32_e32 v4, 0xff, v6
	v_ashrrev_i32_e32 v4, 8, v4
	v_readlane_b32 s12, v253, 61
	v_add_u32_e32 v11, v4, v10
	v_ashrrev_i32_e32 v0, 8, v0
	v_mov_b32_e32 v4, s12
	ds_write_b128 v4, v[8:11]
	v_add_u32_e32 v4, 0xff, v7
	v_ashrrev_i32_e32 v4, 8, v4
	v_add_u32_e32 v4, v4, v11
	v_add_u32_e32 v5, v0, v4
	v_add_u32_e32 v0, 0xff, v1
	v_ashrrev_i32_e32 v0, 8, v0
	v_add_u32_e32 v6, v0, v5
	v_add_u32_e32 v0, 0xff, v2
	v_ashrrev_i32_e32 v0, 8, v0
	v_readlane_b32 s12, v253, 62
	v_add_u32_e32 v7, v0, v6
	s_nop 0
	v_mov_b32_e32 v0, s12
	ds_write_b128 v0, v[4:7]
	v_add_u32_e32 v0, 0xff, v3
	v_ashrrev_i32_e32 v0, 8, v0
	v_readlane_b32 s12, v253, 63
	v_add_u32_e32 v0, v0, v7
	s_nop 0
	v_mov_b32_e32 v1, s12
	ds_write_b32 v1, v0

; #define LAS __attribute__((address_space(3)))
; __device__ __forceinline__ void build_tab(const int* cnt, LAS int* TAB, const int tid) {
;     if (tid == 0) { int s = 0; for (int e = 0; e < NEXP; ++e) { TAB[e] = s; s += (cnt[e] + 255) >> 8; } TAB[NEXP] = s; }
;     __syncthreads();
; }
; __device__ __forceinline__ void run_phase(const Args& a, const int ph, LAS unsigned char* lds, const int tid, const int rpt) {
;     ...
;             } else if (sp == 6) {
;                 build_tab(cnt, TAB, tid);
.LBB0_106:
	v_cmp_eq_u32_e32 vcc, 0, v168
	s_and_saveexec_b64 s[0:1], vcc
	s_cbranch_execz .LBB0_108
	v_readlane_b32 s16, v254, 49
	v_readlane_b32 s17, v254, 50
	s_nop 4
	global_load_dwordx4 v[0:3], v33, s[16:17] offset:48
	global_load_dwordx4 v[4:7], v33, s[16:17] offset:32
	global_load_dwordx4 v[8:11], v33, s[16:17] offset:16
	global_load_dwordx4 v[12:15], v33, s[16:17]
	global_load_dwordx4 v[192:195], v33, s[16:17] offset:112
	global_load_dwordx4 v[196:199], v33, s[16:17] offset:96
	global_load_dwordx4 v[200:203], v33, s[16:17] offset:80
	global_load_dwordx4 v[212:215], v33, s[16:17] offset:64
	v_readlane_b32 s12, v253, 55
	s_waitcnt vmcnt(0)
	v_mov_b32_e32 v16, v33
	s_waitcnt vmcnt(0)
	v_add_u32_e32 v0, 0xff, v0
	v_add_u32_e32 v4, 0xff, v4
	v_add_u32_e32 v8, 0xff, v8
	v_add_u32_e32 v12, 0xff, v12
	v_ashrrev_i32_e32 v17, 8, v12
	v_add_u32_e32 v12, 0xff, v13
	v_ashrrev_i32_e32 v12, 8, v12
	v_add_u32_e32 v18, v12, v17
	v_add_u32_e32 v12, 0xff, v14
	v_ashrrev_i32_e32 v12, 8, v12
	v_add_u32_e32 v19, v12, v18
	v_mov_b32_e32 v12, s12
	ds_write_b128 v12, v[16:19]
	v_add_u32_e32 v12, 0xff, v15
	v_ashrrev_i32_e32 v12, 8, v12
	v_add_u32_e32 v12, v12, v19
	v_ashrrev_i32_e32 v8, 8, v8
	v_add_u32_e32 v13, v8, v12
	v_add_u32_e32 v8, 0xff, v9
	v_ashrrev_i32_e32 v8, 8, v8
	v_add_u32_e32 v14, v8, v13
	v_add_u32_e32 v8, 0xff, v10
	v_ashrrev_i32_e32 v8, 8, v8
	v_readlane_b32 s12, v253, 56
	v_add_u32_e32 v15, v8, v14
	v_ashrrev_i32_e32 v4, 8, v4
	v_mov_b32_e32 v8, s12
	ds_write_b128 v8, v[12:15]
	v_add_u32_e32 v8, 0xff, v11
	v_ashrrev_i32_e32 v8, 8, v8
	v_add_u32_e32 v8, v8, v15
	v_add_u32_e32 v9, v4, v8
	v_add_u32_e32 v4, 0xff, v5
	v_ashrrev_i32_e32 v4, 8, v4
	v_add_u32_e32 v10, v4, v9
	v_add_u32_e32 v4, 0xff, v6
	v_ashrrev_i32_e32 v4, 8, v4
	v_readlane_b32 s12, v253, 57
	v_add_u32_e32 v11, v4, v10
	v_ashrrev_i32_e32 v0, 8, v0
	v_mov_b32_e32 v4, s12
	ds_write_b128 v4, v[8:11]
	v_add_u32_e32 v4, 0xff, v7
	v_ashrrev_i32_e32 v4, 8, v4
	v_add_u32_e32 v4, v4, v11
	v_add_u32_e32 v5, v0, v4
	v_add_u32_e32 v0, 0xff, v1
	v_ashrrev_i32_e32 v0, 8, v0
	v_add_u32_e32 v6, v0, v5
	v_add_u32_e32 v0, 0xff, v2
	v_ashrrev_i32_e32 v0, 8, v0
	v_readlane_b32 s12, v253, 58
	v_add_u32_e32 v7, v0, v6
	s_nop 0
	v_mov_b32_e32 v0, s12
	ds_write_b128 v0, v[4:7]
	v_add_u32_e32 v0, 0xff, v3
	v_ashrrev_i32_e32 v0, 8, v0
	v_add_u32_e32 v12, v0, v7
	v_mov_b64_e32 v[0:1], v[192:193]
	v_mov_b64_e32 v[2:3], v[194:195]
	v_mov_b64_e32 v[4:5], v[196:197]
	v_mov_b64_e32 v[6:7], v[198:199]
	v_mov_b64_e32 v[8:9], v[200:201]
	v_mov_b64_e32 v[10:11], v[202:203]
	v_mov_b64_e32 v[14:15], v[212:213]
	v_mov_b64_e32 v[16:17], v[214:215]
	v_readlane_b32 s12, v253, 59
	s_waitcnt vmcnt(3)
	v_add_u32_e32 v0, 0xff, v0
	s_waitcnt vmcnt(2)
	v_add_u32_e32 v4, 0xff, v4
	s_waitcnt vmcnt(1)
	v_add_u32_e32 v8, 0xff, v8
	s_waitcnt vmcnt(0)
	v_add_u32_e32 v13, 0xff, v14
	v_ashrrev_i32_e32 v13, 8, v13
	v_add_u32_e32 v14, 0xff, v15
	v_add_u32_e32 v13, v13, v12
	v_ashrrev_i32_e32 v14, 8, v14
	v_add_u32_e32 v15, 0xff, v16
	v_add_u32_e32 v14, v14, v13
	v_ashrrev_i32_e32 v15, 8, v15
	v_add_u32_e32 v15, v15, v14
	v_mov_b32_e32 v16, s12
	ds_write_b128 v16, v[12:15]
	v_add_u32_e32 v12, 0xff, v17
	v_ashrrev_i32_e32 v12, 8, v12
	v_add_u32_e32 v12, v12, v15
	v_ashrrev_i32_e32 v8, 8, v8
	v_add_u32_e32 v13, v8, v12
	v_add_u32_e32 v8, 0xff, v9
	v_ashrrev_i32_e32 v8, 8, v8
	v_add_u32_e32 v14, v8, v13
	v_add_u32_e32 v8, 0xff, v10
	v_ashrrev_i32_e32 v8, 8, v8
	v_readlane_b32 s12, v253, 60
	v_add_u32_e32 v15, v8, v14
	v_ashrrev_i32_e32 v4, 8, v4
	v_mov_b32_e32 v8, s12
	ds_write_b128 v8, v[12:15]
	v_add_u32_e32 v8, 0xff, v11
	v_ashrrev_i32_e32 v8, 8, v8
	v_add_u32_e32 v8, v8, v15
	v_add_u32_e32 v9, v4, v8
	v_add_u32_e32 v4, 0xff, v5
	v_ashrrev_i32_e32 v4, 8, v4
	v_add_u32_e32 v10, v4, v9
	v_add_u32_e32 v4, 0xff, v6
	v_ashrrev_i32_e32 v4, 8, v4
	v_readlane_b32 s12, v253, 61
	v_add_u32_e32 v11, v4, v10
	v_ashrrev_i32_e32 v0, 8, v0
	v_mov_b32_e32 v4, s12
	ds_write_b128 v4, v[8:11]
	v_add_u32_e32 v4, 0xff, v7
	v_ashrrev_i32_e32 v4, 8, v4
	v_add_u32_e32 v4, v4, v11
	v_add_u32_e32 v5, v0, v4
	v_add_u32_e32 v0, 0xff, v1
	v_ashrrev_i32_e32 v0, 8, v0
	v_add_u32_e32 v6, v0, v5
	v_add_u32_e32 v0, 0xff, v2
	v_ashrrev_i32_e32 v0, 8, v0
	v_readlane_b32 s12, v253, 62
	v_add_u32_e32 v7, v0, v6
	s_nop 0
	v_mov_b32_e32 v0, s12
	ds_write_b128 v0, v[4:7]
	v_add_u32_e32 v0, 0xff, v3
	v_ashrrev_i32_e32 v0, 8, v0
	v_readlane_b32 s12, v253, 63
	v_add_u32_e32 v0, v0, v7
	s_nop 0
	v_mov_b32_e32 v1, s12
	ds_write_b32 v1, v0
